# split 38 plain v_pk_add_f32 between MFMAs in A-unit code into scalar v_add_f32 (bit-identical)
# speedup vs baseline: 1.0014x; 1.0014x over previous
.LBB0_344:
	s_or_b64 exec, exec, s[10:11]
	v_add_u32_e32 v168, s49, v209
	v_lshlrev_b32_e32 v168, s47, v168
	s_lshl_b32 s14, s26, 6
	v_add_u32_e32 v128, s48, v168
	v_mov_b64_e32 v[166:167], s[0:1]
	v_mad_i64_i32 v[166:167], s[10:11], v128, s35, v[166:167]
	s_lshl_b32 s14, s14, 1
	v_lshl_add_u64 v[166:167], v[166:167], 0, s[14:15]
	v_lshlrev_b32_e32 v168, 1, v176
	v_mov_b32_e32 v169, 0
	v_lshl_add_u64 v[166:167], v[166:167], 0, v[168:169]
	global_load_dwordx4 v[112:115], v[166:167], off
	global_load_dwordx4 v[116:119], v[166:167], off offset:32
	global_load_dwordx4 v[120:123], v[166:167], off offset:64
	global_load_dwordx4 v[124:127], v[166:167], off offset:96
	s_waitcnt vmcnt(5)
	v_add_u32_e32 v0, v206, v207
	s_waitcnt vmcnt(4)
	ds_write_b128 v0, v[6:9]
	v_add_u32_e32 v6, v206, v208
	ds_write_b128 v6, v[10:13] offset:55296
	ds_write_b128 v0, v[14:17] offset:9216
	ds_write_b128 v196, v[18:21] offset:55296
	ds_write_b128 v0, v[22:25] offset:18432
	ds_write_b128 v202, v[2:5] offset:55296
	ds_write_b128 v0, v[34:37] offset:27648
	ds_write_b128 v203, v[30:33] offset:55296
	ds_write_b128 v0, v[38:41] offset:36864
	ds_write_b128 v204, v[26:29] offset:55296
	ds_write_b128 v0, v[46:49] offset:46080
	ds_write_b128 v238, v[42:45] offset:55296
	v_readlane_b32 s10, v254, 41
	s_cmp_eq_u32 s43, 0
	s_nop 0
	v_mov_b32_e32 v0, s10
	ds_read_b32 v0, v0
	s_waitcnt lgkmcnt(0)
	s_barrier
	v_xor_b32_e32 v16, 0x80000000, v0
	s_cbranch_scc1 .LBB0_347
	ds_read_b64_tr_b16 v[2:3], v240 offset:55296
	ds_read_b64_tr_b16 v[4:5], v240 offset:56832
	ds_read_b64_tr_b16 v[6:7], v240 offset:58368
	ds_read_b64_tr_b16 v[8:9], v240 offset:59904
	ds_read_b64_tr_b16 v[10:11], v240 offset:55360
	ds_read_b64_tr_b16 v[12:13], v240 offset:56896
	ds_read_b64_tr_b16 v[64:65], v240 offset:58432
	ds_read_b64_tr_b16 v[66:67], v240 offset:59968
	ds_read_b128 v[48:51], v239 offset:96
	ds_read_b128 v[52:55], v239 offset:64
	ds_read_b128 v[56:59], v239
	ds_read_b128 v[60:63], v239 offset:32
	v_mov_b32_e32 v17, v16
	v_mov_b32_e32 v18, v16
	v_mov_b32_e32 v19, v16
	v_mov_b32_e32 v20, v16
	v_mov_b32_e32 v21, v16
	v_mov_b32_e32 v22, v16
	v_mov_b32_e32 v23, v16
	v_mov_b32_e32 v24, v16
	v_mov_b32_e32 v25, v16
	v_mov_b32_e32 v26, v16
	v_mov_b32_e32 v27, v16
	v_mov_b32_e32 v28, v16
	v_mov_b32_e32 v29, v16
	v_mov_b32_e32 v30, v16
	v_mov_b32_e32 v31, v16
	s_waitcnt lgkmcnt(0)
	v_readlane_b32 s10, v254, 50
	v_readlane_b32 s11, v254, 51
	s_waitcnt vmcnt(3)
	v_mfma_f32_32x32x16_bf16 v[32:47], v[56:59], v[112:115], v[16:31]
	s_waitcnt vmcnt(2)
	v_mfma_f32_32x32x16_bf16 v[32:47], v[60:63], v[116:119], v[32:47]
	s_waitcnt vmcnt(1)
	v_mfma_f32_32x32x16_bf16 v[32:47], v[52:55], v[120:123], v[32:47]
	s_waitcnt vmcnt(0)
	v_mfma_f32_32x32x16_bf16 v[32:47], v[48:51], v[124:127], v[32:47]
	s_nop 11
	v_cndmask_b32_e64 v0, v32, v201, s[72:73]
	v_cndmask_b32_e64 v32, v35, v201, s[10:11]
	v_readlane_b32 s10, v254, 52
	v_readlane_b32 s11, v254, 53
	v_cndmask_b32_e64 v14, v33, v201, s[74:75]
	v_cndmask_b32_e64 v15, v34, v201, s[78:79]
	v_cndmask_b32_e64 v33, v36, v201, s[10:11]
	v_readlane_b32 s10, v254, 54
	v_readlane_b32 s11, v254, 55
	v_exp_f32_e32 v0, v0
	v_exp_f32_e32 v14, v14
	v_cndmask_b32_e64 v34, v37, v201, s[10:11]
	v_readlane_b32 s10, v254, 56
	v_readlane_b32 s11, v254, 57
	v_exp_f32_e32 v15, v15
	v_exp_f32_e32 v34, v34
	v_cndmask_b32_e64 v35, v38, v201, s[10:11]
	v_readlane_b32 s10, v254, 58
	v_readlane_b32 s11, v254, 59
	v_exp_f32_e32 v35, v35
	s_nop 0
	v_cndmask_b32_e64 v36, v39, v201, s[10:11]
	v_readlane_b32 s10, v254, 60
	v_readlane_b32 s11, v254, 61
	v_exp_f32_e32 v36, v36
	s_nop 0
	v_cndmask_b32_e64 v37, v40, v201, s[10:11]
	v_readlane_b32 s10, v254, 62
	v_readlane_b32 s11, v254, 63
	v_exp_f32_e32 v37, v37
	s_nop 0
	v_cndmask_b32_e64 v38, v41, v201, s[10:11]
	v_readlane_b32 s10, v255, 0
	v_readlane_b32 s11, v255, 1
	v_exp_f32_e32 v38, v38
	s_nop 0
	v_cndmask_b32_e64 v39, v42, v201, s[10:11]
	v_readlane_b32 s10, v255, 2
	v_readlane_b32 s11, v255, 3
	v_exp_f32_e32 v39, v39
	s_nop 0
	v_cndmask_b32_e64 v40, v43, v201, s[10:11]
	v_readlane_b32 s10, v255, 4
	v_readlane_b32 s11, v255, 5
	v_exp_f32_e32 v40, v40
	s_nop 0
	v_cndmask_b32_e64 v41, v44, v201, s[10:11]
	v_readlane_b32 s10, v255, 6
	v_readlane_b32 s11, v255, 7
	v_exp_f32_e32 v41, v41
	s_nop 0
	v_cndmask_b32_e64 v42, v45, v201, s[10:11]
	v_readlane_b32 s10, v255, 8
	v_readlane_b32 s11, v255, 9
	v_add_f32_e32 v45, 0, v0
	v_add_f32_e32 v45, v14, v45
	v_cndmask_b32_e64 v43, v46, v201, s[10:11]
	v_exp_f32_e32 v46, v32
	v_add_f32_e32 v45, v15, v45
	v_readlane_b32 s10, v255, 10
	v_readlane_b32 s11, v255, 11
	v_add_f32_e32 v32, v46, v45
	v_exp_f32_e32 v45, v33
	v_exp_f32_e32 v42, v42
	v_cndmask_b32_e64 v44, v47, v201, s[10:11]
	v_exp_f32_e32 v43, v43
	v_add_f32_e32 v32, v45, v32
	v_add_f32_e32 v32, v34, v32
	v_add_f32_e32 v32, v35, v32
	v_add_f32_e32 v32, v36, v32
	v_add_f32_e32 v32, v37, v32
	v_add_f32_e32 v32, v38, v32
	v_add_f32_e32 v32, v39, v32
	v_add_f32_e32 v32, v40, v32
	v_exp_f32_e32 v44, v44
	v_add_f32_e32 v32, v41, v32
	v_add_f32_e32 v32, v42, v32
	v_add_f32_e32 v32, v43, v32
	v_add_f32_e32 v129, v44, v32
	v_cvt_pk_bf16_f32 v32, v0, v14
	v_cvt_pk_bf16_f32 v33, v15, v46
	v_cvt_pk_bf16_f32 v34, v45, v34
	v_cvt_pk_bf16_f32 v35, v35, v36
	v_cvt_pk_bf16_f32 v68, v37, v38
	v_cvt_pk_bf16_f32 v69, v39, v40
	v_cvt_pk_bf16_f32 v70, v41, v42
	v_cvt_pk_bf16_f32 v71, v43, v44
	s_nop 0
	v_mfma_f32_32x32x16_bf16 v[48:63], v[2:5], v[32:35], 0
	v_mfma_f32_32x32x16_bf16 v[32:47], v[10:13], v[32:35], 0
	v_mfma_f32_32x32x16_bf16 v[48:63], v[6:9], v[68:71], v[48:63]
	v_mfma_f32_32x32x16_bf16 v[32:47], v[64:67], v[68:71], v[32:47]
	ds_read_b128 v[2:5], v241 offset:96
	ds_read_b128 v[6:9], v241 offset:64
	ds_read_b128 v[10:13], v241
	ds_read_b128 v[130:133], v241 offset:32
	ds_read_b128 v[134:137], v241 offset:4704
	ds_read_b128 v[138:141], v241 offset:4672
	ds_read_b128 v[142:145], v241 offset:4640
	ds_read_b128 v[64:67], v241 offset:4608
	ds_read_b128 v[146:149], v241 offset:9312
	ds_read_b128 v[150:153], v241 offset:9280
	ds_read_b128 v[154:157], v241 offset:9248
	ds_read_b128 v[158:161], v241 offset:9216
	s_waitcnt lgkmcnt(8)
	s_waitcnt lgkmcnt(4)
	s_waitcnt lgkmcnt(0)
	v_mfma_f32_32x32x16_bf16 v[96:111], v[10:13], v[112:115], v[16:31]
	v_mfma_f32_32x32x16_bf16 v[80:95], v[64:67], v[112:115], v[16:31]
	v_mfma_f32_32x32x16_bf16 v[96:111], v[130:133], v[116:119], v[96:111]
	v_mfma_f32_32x32x16_bf16 v[64:79], v[158:161], v[112:115], v[16:31]
	v_mfma_f32_32x32x16_bf16 v[80:95], v[142:145], v[116:119], v[80:95]
	v_mfma_f32_32x32x16_bf16 v[96:111], v[6:9], v[120:123], v[96:111]
	v_mfma_f32_32x32x16_bf16 v[64:79], v[154:157], v[116:119], v[64:79]
	v_mfma_f32_32x32x16_bf16 v[80:95], v[138:141], v[120:123], v[80:95]
	v_mfma_f32_32x32x16_bf16 v[96:111], v[2:5], v[124:127], v[96:111]
	ds_read_b64_tr_b16 v[2:3], v242 offset:55296
	ds_read_b64_tr_b16 v[4:5], v242 offset:56832
	ds_read_b64_tr_b16 v[6:7], v243 offset:55296
	ds_read_b64_tr_b16 v[8:9], v243 offset:56832
	ds_read_b64_tr_b16 v[10:11], v242 offset:55360
	ds_read_b64_tr_b16 v[12:13], v242 offset:56896
	ds_read_b64_tr_b16 v[130:131], v243 offset:55360
	ds_read_b64_tr_b16 v[132:133], v243 offset:56896
	v_mfma_f32_32x32x16_bf16 v[64:79], v[150:153], v[120:123], v[64:79]
	v_mfma_f32_32x32x16_bf16 v[80:95], v[134:137], v[124:127], v[80:95]
	v_mfma_f32_32x32x16_bf16 v[64:79], v[146:149], v[124:127], v[64:79]
	s_nop 0
	v_exp_f32_e32 v0, v96
	v_exp_f32_e32 v134, v97
	v_exp_f32_e32 v136, v98
	v_exp_f32_e32 v138, v99
	v_exp_f32_e32 v140, v100
	v_exp_f32_e32 v142, v101
	v_exp_f32_e32 v144, v102
	v_exp_f32_e32 v146, v103
	v_exp_f32_e32 v148, v104
	v_exp_f32_e32 v150, v105
	v_exp_f32_e32 v152, v106
	v_exp_f32_e32 v154, v107
	v_exp_f32_e32 v156, v108
	v_exp_f32_e32 v158, v109
	v_exp_f32_e32 v160, v110
	v_exp_f32_e32 v162, v111
	v_cvt_pk_bf16_f32 v96, v0, v134
	v_cvt_pk_bf16_f32 v97, v136, v138
	v_cvt_pk_bf16_f32 v98, v140, v142
	v_cvt_pk_bf16_f32 v99, v144, v146
	v_cvt_pk_bf16_f32 v100, v148, v150
	v_cvt_pk_bf16_f32 v101, v152, v154
	v_cvt_pk_bf16_f32 v102, v156, v158
	v_cvt_pk_bf16_f32 v103, v160, v162
	s_waitcnt lgkmcnt(0)
	s_nop 0
	v_mfma_f32_32x32x16_bf16 v[48:63], v[2:5], v[96:99], v[48:63]
	v_mfma_f32_32x32x16_bf16 v[32:47], v[10:13], v[96:99], v[32:47]
	v_mfma_f32_32x32x16_bf16 v[48:63], v[6:9], v[100:103], v[48:63]
	ds_read_b64_tr_b16 v[2:3], v244 offset:55296
	ds_read_b64_tr_b16 v[4:5], v244 offset:56832
	ds_read_b64_tr_b16 v[8:9], v244 offset:56896
	ds_read_b64_tr_b16 v[6:7], v244 offset:55360
	ds_read_b64_tr_b16 v[10:11], v245 offset:55296
	ds_read_b64_tr_b16 v[12:13], v245 offset:56832
	ds_read_b64_tr_b16 v[98:99], v245 offset:56896
	ds_read_b64_tr_b16 v[96:97], v245 offset:55360
	v_mfma_f32_32x32x16_bf16 v[32:47], v[130:133], v[100:103], v[32:47]
	v_exp_f32_e32 v135, v80
	v_exp_f32_e32 v137, v81
	v_exp_f32_e32 v139, v82
	v_exp_f32_e32 v141, v83
	v_exp_f32_e32 v143, v84
	v_exp_f32_e32 v145, v85
	v_exp_f32_e32 v147, v86
	v_exp_f32_e32 v149, v87
	v_exp_f32_e32 v151, v88
	v_exp_f32_e32 v153, v89
	v_exp_f32_e32 v155, v90
	v_exp_f32_e32 v157, v91
	v_exp_f32_e32 v159, v92
	v_exp_f32_e32 v161, v93
	v_exp_f32_e32 v163, v94
	v_exp_f32_e32 v131, v95
	v_cvt_pk_bf16_f32 v80, v135, v137
	v_cvt_pk_bf16_f32 v81, v139, v141
	v_cvt_pk_bf16_f32 v82, v143, v145
	v_cvt_pk_bf16_f32 v83, v147, v149
	v_cvt_pk_bf16_f32 v84, v151, v153
	v_cvt_pk_bf16_f32 v85, v155, v157
	v_cvt_pk_bf16_f32 v86, v159, v161
	v_cvt_pk_bf16_f32 v87, v163, v131
	s_waitcnt lgkmcnt(0)
	s_nop 0
	v_mfma_f32_32x32x16_bf16 v[48:63], v[2:5], v[80:83], v[48:63]
	v_mfma_f32_32x32x16_bf16 v[32:47], v[6:9], v[80:83], v[32:47]
	v_mfma_f32_32x32x16_bf16 v[48:63], v[10:13], v[84:87], v[48:63]
	ds_read_b64_tr_b16 v[2:3], v246 offset:55296
	ds_read_b64_tr_b16 v[4:5], v246 offset:56832
	ds_read_b64_tr_b16 v[8:9], v246 offset:56896
	ds_read_b64_tr_b16 v[6:7], v246 offset:55360
	ds_read_b64_tr_b16 v[10:11], v247 offset:55296
	ds_read_b64_tr_b16 v[12:13], v247 offset:56832
	ds_read_b64_tr_b16 v[82:83], v247 offset:56896
	ds_read_b64_tr_b16 v[80:81], v247 offset:55360
	v_mfma_f32_32x32x16_bf16 v[32:47], v[96:99], v[84:87], v[32:47]
	v_exp_f32_e32 v15, v64
	v_exp_f32_e32 v84, v65
	v_exp_f32_e32 v92, v66
	v_exp_f32_e32 v90, v67
	v_exp_f32_e32 v100, v68
	v_exp_f32_e32 v98, v69
	v_exp_f32_e32 v108, v70
	v_exp_f32_e32 v106, v71
	v_exp_f32_e32 v110, v72
	v_exp_f32_e32 v14, v73
	v_exp_f32_e32 v88, v74
	v_exp_f32_e32 v86, v75
	v_exp_f32_e32 v96, v76
	v_exp_f32_e32 v94, v77
	v_exp_f32_e32 v104, v78
	v_exp_f32_e32 v102, v79
	v_cvt_pk_bf16_f32 v64, v15, v84
	v_cvt_pk_bf16_f32 v65, v92, v90
	v_cvt_pk_bf16_f32 v66, v100, v98
	v_cvt_pk_bf16_f32 v67, v108, v106
	v_cvt_pk_bf16_f32 v68, v110, v14
	v_cvt_pk_bf16_f32 v69, v88, v86
	v_cvt_pk_bf16_f32 v70, v96, v94
	v_cvt_pk_bf16_f32 v71, v104, v102
	s_waitcnt lgkmcnt(0)
	v_add_f32_e32 v0, 0, v0
	v_mfma_f32_32x32x16_bf16 v[48:63], v[2:5], v[64:67], v[48:63]
	v_add_f32_e64 v2, v134, v0
	v_add_f32_e64 v3, v135, v1
	v_add_f32_e32 v130, 0, v129
	v_add_f32_e64 v2, v136, v2
	v_add_f32_e64 v3, v137, v3
	v_readlane_b32 s10, v255, 12
	v_add_f32_e32 v2, v138, v2
	v_add_f32_e32 v3, v139, v3
	v_readlane_b32 s11, v255, 13
	v_add_f32_e32 v2, v140, v2
	v_add_f32_e32 v3, v141, v3
	v_mfma_f32_32x32x16_bf16 v[32:47], v[6:9], v[64:67], v[32:47]
	v_add_f32_e64 v2, v142, v2
	v_add_f32_e64 v3, v143, v3
	v_add_f32_e32 v0, 0, v15
	v_add_f32_e64 v2, v144, v2
	v_add_f32_e64 v3, v145, v3
	v_add_f32_e32 v2, v146, v2
	v_add_f32_e32 v3, v147, v3
	s_nop 0
	v_add_f32_e32 v2, v148, v2
	v_add_f32_e32 v3, v149, v3
	v_mfma_f32_32x32x16_bf16 v[48:63], v[10:13], v[68:71], v[48:63]
	v_add_f32_e64 v2, v150, v2
	v_add_f32_e64 v3, v151, v3
	v_add_f32_e64 v2, v152, v2
	v_add_f32_e64 v3, v153, v3
	v_add_f32_e64 v2, v154, v2
	v_add_f32_e64 v3, v155, v3
	v_add_f32_e32 v2, v156, v2
	v_add_f32_e32 v3, v157, v3
	v_mfma_f32_32x32x16_bf16 v[32:47], v[80:83], v[68:71], v[32:47]
	v_add_f32_e64 v2, v158, v2
	v_add_f32_e64 v3, v159, v3
	v_mov_b64_e32 v[78:79], v[30:31]
	v_add_f32_e64 v2, v160, v2
	v_add_f32_e64 v3, v161, v3
	v_mov_b64_e32 v[76:77], v[28:29]
	v_add_f32_e32 v2, v162, v2
	v_add_f32_e32 v3, v163, v3
	v_mov_b64_e32 v[74:75], v[26:27]
	v_add_f32_e32 v130, v130, v2
	v_add_f32_e32 v131, v131, v3
	ds_read_b64_tr_b16 v[80:81], v249 offset:55296
	ds_read_b64_tr_b16 v[82:83], v249 offset:56832
	ds_read_b64_tr_b16 v[10:11], v250 offset:55296
	ds_read_b64_tr_b16 v[12:13], v250 offset:56832
	ds_read_b64_tr_b16 v[6:7], v249 offset:55360
	ds_read_b64_tr_b16 v[8:9], v249 offset:56896
	ds_read_b64_tr_b16 v[2:3], v250 offset:55360
	ds_read_b64_tr_b16 v[4:5], v250 offset:56896
	ds_read_b128 v[132:135], v248 offset:96
	ds_read_b128 v[136:139], v248 offset:64
	ds_read_b128 v[140:143], v248
	ds_read_b128 v[144:147], v248 offset:32
	v_mov_b64_e32 v[72:73], v[24:25]
	v_mov_b64_e32 v[70:71], v[22:23]
	v_mov_b64_e32 v[68:69], v[20:21]
	v_mov_b64_e32 v[66:67], v[18:19]
	v_mov_b64_e32 v[64:65], v[16:17]
	s_waitcnt lgkmcnt(0)
	s_nop 0
	v_mfma_f32_32x32x16_bf16 v[64:79], v[140:143], v[112:115], v[64:79]
	v_mfma_f32_32x32x16_bf16 v[64:79], v[144:147], v[116:119], v[64:79]
	v_mfma_f32_32x32x16_bf16 v[64:79], v[136:139], v[120:123], v[64:79]
	v_mfma_f32_32x32x16_bf16 v[64:79], v[132:135], v[124:127], v[64:79]
	s_nop 11
	v_cndmask_b32_e64 v15, v64, v201, s[10:11]
	v_readlane_b32 s10, v255, 14
	v_readlane_b32 s11, v255, 15
	v_cndmask_b32_e64 v15, v15, v64, s[44:45]
	v_cndmask_b32_e64 v17, v201, v65, s[44:45]
	v_cndmask_b32_e64 v18, v66, v201, s[10:11]
	v_readlane_b32 s10, v255, 16
	v_readlane_b32 s11, v255, 17
	v_exp_f32_e32 v85, v15
	v_exp_f32_e32 v93, v17
	v_cndmask_b32_e64 v19, v67, v201, s[10:11]
	v_readlane_b32 s10, v255, 18
	v_readlane_b32 s11, v255, 19
	v_exp_f32_e32 v91, v18
	v_exp_f32_e32 v101, v19
	v_cndmask_b32_e64 v20, v68, v201, s[10:11]
	v_readlane_b32 s10, v255, 20
	v_readlane_b32 s11, v255, 21
	v_add_f32_e32 v18, v84, v0
	v_add_f32_e32 v19, v85, v1
	v_exp_f32_e32 v99, v20
	v_cndmask_b32_e64 v21, v69, v201, s[10:11]
	v_readlane_b32 s10, v255, 22
	v_readlane_b32 s11, v255, 23
	v_add_f32_e32 v18, v92, v18
	v_add_f32_e32 v19, v93, v19
	v_exp_f32_e32 v109, v21
	v_cndmask_b32_e64 v22, v70, v201, s[10:11]
	v_cndmask_b32_e64 v23, v71, v201, s[56:57]
	v_add_f32_e32 v18, v90, v18
	v_add_f32_e32 v19, v91, v19
	v_exp_f32_e32 v107, v22
	v_cndmask_b32_e64 v24, v72, v201, s[58:59]
	v_add_f32_e32 v18, v100, v18
	v_add_f32_e32 v19, v101, v19
	v_exp_f32_e32 v111, v23
	v_cndmask_b32_e64 v25, v73, v201, s[60:61]
	v_exp_f32_e32 v15, v24
	v_add_f32_e32 v18, v98, v18
	v_add_f32_e32 v19, v99, v19
	v_cndmask_b32_e64 v26, v74, v201, s[62:63]
	v_exp_f32_e32 v89, v25
	v_add_f32_e32 v18, v108, v18
	v_add_f32_e32 v19, v109, v19
	v_cndmask_b32_e64 v27, v75, v201, s[64:65]
	v_exp_f32_e32 v87, v26
	v_add_f32_e32 v18, v106, v18
	v_add_f32_e32 v19, v107, v19
	v_cndmask_b32_e64 v28, v76, v201, s[66:67]
	v_exp_f32_e32 v97, v27
	v_add_f32_e32 v18, v110, v18
	v_add_f32_e32 v19, v111, v19
	v_cndmask_b32_e64 v29, v77, v201, s[40:41]
	v_exp_f32_e32 v95, v28
	v_add_f32_e32 v18, v14, v18
	v_add_f32_e32 v19, v15, v19
	v_cndmask_b32_e64 v30, v78, v201, s[8:9]
	v_cndmask_b32_e64 v31, v79, v201, s[4:5]
	v_exp_f32_e32 v105, v29
	v_add_f32_e32 v18, v88, v18
	v_add_f32_e32 v19, v89, v19
	v_exp_f32_e32 v103, v30
	v_exp_f32_e32 v0, v31
	v_add_f32_e32 v18, v86, v18
	v_add_f32_e32 v19, v87, v19
	v_pk_add_f32 v[20:21], v[130:131], v[130:131] op_sel:[0,1] op_sel_hi:[1,0]
	v_add_f32_e32 v18, v96, v18
	v_add_f32_e32 v19, v97, v19
	v_mov_b32_e32 v21, v0
	v_add_f32_e32 v18, v94, v18
	v_add_f32_e32 v19, v95, v19
	s_nop 0
	v_add_f32_e32 v18, v104, v18
	v_add_f32_e32 v19, v105, v19
	s_nop 0
	v_add_f32_e32 v18, v102, v18
	v_add_f32_e32 v19, v103, v19
	s_nop 0
	v_add_f32_e32 v18, v20, v18
	v_add_f32_e32 v19, v21, v19
	s_nop 0
	v_add_f32_e32 v84, v18, v19
	v_cvt_pk_bf16_f32 v18, v85, v93
	v_cvt_pk_bf16_f32 v19, v91, v101
	v_cvt_pk_bf16_f32 v20, v99, v109
	v_cvt_pk_bf16_f32 v21, v107, v111
	v_cvt_pk_bf16_f32 v22, v15, v89
	v_cvt_pk_bf16_f32 v23, v87, v97
	v_cvt_pk_bf16_f32 v24, v95, v105
	v_cvt_pk_bf16_f32 v25, v103, v0
	s_nop 0
	v_mfma_f32_32x32x16_bf16 v[48:63], v[80:83], v[18:21], v[48:63]
	v_mfma_f32_32x32x16_bf16 v[32:47], v[6:9], v[18:21], v[32:47]
	v_mfma_f32_32x32x16_bf16 v[48:63], v[10:13], v[22:25], v[48:63]
	v_mfma_f32_32x32x16_bf16 v[32:47], v[2:5], v[22:25], v[32:47]
	s_cbranch_execz .LBB0_348
	s_branch .LBB0_352

.LBB0_391:
	s_and_b64 vcc, exec, s[10:11]
	s_cbranch_vccz .LBB0_393
	ds_read_b128 v[2:5], v0 offset:96
	ds_read_b128 v[6:9], v0 offset:64
	ds_read_b128 v[10:13], v0
	ds_read_b128 v[32:35], v0 offset:32
	ds_read_b128 v[36:39], v0 offset:224
	ds_read_b128 v[40:43], v0 offset:192
	ds_read_b128 v[112:115], v0 offset:160
	ds_read_b128 v[116:119], v0 offset:128
	s_waitcnt lgkmcnt(4)
	v_add3_u32 v234, s86, v229, v227
	v_sub_f32_e32 v111, v63, v5
	v_sub_f32_e32 v110, v62, v4
	v_sub_f32_e32 v109, v61, v3
	v_sub_f32_e32 v108, v60, v2
	v_sub_f32_e32 v107, v59, v9
	v_sub_f32_e32 v106, v58, v8
	v_sub_f32_e32 v105, v57, v7
	v_sub_f32_e32 v104, v56, v6
	v_sub_f32_e32 v103, v55, v35
	v_sub_f32_e32 v102, v54, v34
	v_sub_f32_e32 v101, v53, v33
	v_sub_f32_e32 v100, v52, v32
	v_sub_f32_e32 v99, v51, v13
	v_sub_f32_e32 v98, v50, v12
	v_sub_f32_e32 v97, v49, v11
	v_sub_f32_e32 v96, v48, v10
	s_waitcnt lgkmcnt(0)
	ds_read_b128 v[2:5], v234 offset:96
	ds_read_b128 v[6:9], v234 offset:64
	ds_read_b128 v[10:13], v234
	ds_read_b128 v[120:123], v234 offset:32
	ds_read_b128 v[124:127], v234 offset:4704
	ds_read_b128 v[128:131], v234 offset:4672
	ds_read_b128 v[132:135], v234 offset:4640
	ds_read_b128 v[136:139], v234 offset:4608
	s_waitcnt lgkmcnt(4)
	v_sub_f32_e32 v47, v63, v39
	v_mfma_f32_32x32x16_bf16 v[96:111], v[10:13], v[144:147], v[96:111]
	v_sub_f32_e32 v46, v62, v38
	v_sub_f32_e32 v45, v61, v37
	v_sub_f32_e32 v44, v60, v36
	v_sub_f32_e32 v43, v59, v43
	v_sub_f32_e32 v42, v58, v42
	v_sub_f32_e32 v41, v57, v41
	v_sub_f32_e32 v40, v56, v40
	v_sub_f32_e32 v39, v55, v115
	v_sub_f32_e32 v38, v54, v114
	v_sub_f32_e32 v37, v53, v113
	v_sub_f32_e32 v36, v52, v112
	v_sub_f32_e32 v35, v51, v119
	v_sub_f32_e32 v34, v50, v118
	v_sub_f32_e32 v33, v49, v117
	v_sub_f32_e32 v32, v48, v116
	s_waitcnt lgkmcnt(0)
	v_mfma_f32_32x32x16_bf16 v[96:111], v[120:123], v[148:151], v[96:111]
	v_mfma_f32_32x32x16_bf16 v[32:47], v[136:139], v[144:147], v[32:47]
	v_mfma_f32_32x32x16_bf16 v[32:47], v[132:135], v[148:151], v[32:47]
	v_mfma_f32_32x32x16_bf16 v[96:111], v[6:9], v[152:155], v[96:111]
	v_mfma_f32_32x32x16_bf16 v[32:47], v[128:131], v[152:155], v[32:47]
	v_mfma_f32_32x32x16_bf16 v[96:111], v[2:5], v[156:159], v[96:111]
	v_add3_u32 v4, s77, v230, v211
	ds_read_b64_tr_b16 v[6:7], v4 offset:36864
	ds_read_b64_tr_b16 v[8:9], v4 offset:38400
	ds_read_b64_tr_b16 v[12:13], v4 offset:38464
	ds_read_b64_tr_b16 v[10:11], v4 offset:36928
	ds_read_b64_tr_b16 v[112:113], v4 offset:39936
	ds_read_b64_tr_b16 v[114:115], v4 offset:41472
	ds_read_b64_tr_b16 v[118:119], v4 offset:41536
	ds_read_b64_tr_b16 v[116:117], v4 offset:40000
	v_mfma_f32_32x32x16_bf16 v[32:47], v[124:127], v[156:159], v[32:47]
	s_nop 1
	v_exp_f32_e32 v2, v96
	v_exp_f32_e32 v15, v97
	v_exp_f32_e32 v121, v98
	v_exp_f32_e32 v123, v99
	v_exp_f32_e32 v125, v100
	v_exp_f32_e32 v127, v101
	v_exp_f32_e32 v129, v102
	v_exp_f32_e32 v131, v103
	v_exp_f32_e32 v133, v104
	v_exp_f32_e32 v135, v105
	v_exp_f32_e32 v137, v106
	v_exp_f32_e32 v139, v107
	v_exp_f32_e32 v141, v108
	v_exp_f32_e32 v109, v109
	v_exp_f32_e32 v143, v110
	v_exp_f32_e32 v111, v111
	v_cvt_pk_bf16_f32 v96, v2, v15
	v_cvt_pk_bf16_f32 v97, v121, v123
	v_cvt_pk_bf16_f32 v98, v125, v127
	v_cvt_pk_bf16_f32 v99, v129, v131
	v_cvt_pk_bf16_f32 v100, v133, v135
	v_cvt_pk_bf16_f32 v101, v137, v139
	v_cvt_pk_bf16_f32 v102, v141, v109
	v_cvt_pk_bf16_f32 v103, v143, v111
	s_waitcnt lgkmcnt(0)
	v_add_f32_e32 v3, 0, v2
	v_mfma_f32_32x32x16_bf16 v[64:79], v[6:9], v[96:99], v[64:79]
	v_mfma_f32_32x32x16_bf16 v[80:95], v[10:13], v[96:99], v[80:95]
	ds_read_b64_tr_b16 v[6:7], v4 offset:43008
	ds_read_b64_tr_b16 v[8:9], v4 offset:44544
	ds_read_b64_tr_b16 v[12:13], v4 offset:44608
	ds_read_b64_tr_b16 v[10:11], v4 offset:43072
	ds_read_b64_tr_b16 v[96:97], v4 offset:46080
	ds_read_b64_tr_b16 v[98:99], v4 offset:47616
	ds_read_b64_tr_b16 v[106:107], v4 offset:47680
	ds_read_b64_tr_b16 v[104:105], v4 offset:46144
	v_mfma_f32_32x32x16_bf16 v[64:79], v[112:115], v[100:103], v[64:79]
	v_mfma_f32_32x32x16_bf16 v[80:95], v[116:119], v[100:103], v[80:95]
	v_exp_f32_e32 v14, v32
	v_exp_f32_e32 v120, v33
	v_exp_f32_e32 v122, v34
	v_exp_f32_e32 v124, v35
	v_mov_b32_e32 v2, v1
	v_add_f32_e32 v2, v14, v2
	v_add_f32_e32 v3, v15, v3
	v_exp_f32_e32 v126, v36
	v_add_f32_e32 v2, v120, v2
	v_add_f32_e32 v3, v121, v3
	v_exp_f32_e32 v128, v37
	v_add_f32_e32 v2, v122, v2
	v_add_f32_e32 v3, v123, v3
	v_exp_f32_e32 v130, v38
	v_add_f32_e32 v2, v124, v2
	v_add_f32_e32 v3, v125, v3
	v_exp_f32_e32 v132, v39
	v_exp_f32_e32 v134, v40
	v_add_f32_e32 v2, v126, v2
	v_add_f32_e32 v3, v127, v3
	v_exp_f32_e32 v136, v41
	v_add_f32_e32 v2, v128, v2
	v_add_f32_e32 v3, v129, v3
	v_exp_f32_e32 v138, v42
	v_exp_f32_e32 v140, v43
	v_exp_f32_e32 v108, v44
	v_exp_f32_e32 v142, v45
	v_exp_f32_e32 v110, v46
	v_exp_f32_e32 v192, v47
	v_add_f32_e32 v2, v130, v2
	v_add_f32_e32 v3, v131, v3
	v_cvt_pk_bf16_f32 v32, v14, v120
	v_cvt_pk_bf16_f32 v33, v122, v124
	v_cvt_pk_bf16_f32 v34, v126, v128
	v_cvt_pk_bf16_f32 v35, v130, v132
	v_cvt_pk_bf16_f32 v36, v134, v136
	v_cvt_pk_bf16_f32 v37, v138, v140
	v_cvt_pk_bf16_f32 v38, v108, v142
	v_cvt_pk_bf16_f32 v39, v110, v192
	s_waitcnt lgkmcnt(0)
	v_add_f32_e32 v2, v132, v2
	v_add_f32_e32 v3, v133, v3
	v_mfma_f32_32x32x16_bf16 v[64:79], v[6:9], v[32:35], v[64:79]
	v_add_f32_e64 v2, v134, v2
	v_add_f32_e64 v3, v135, v3
	v_add_f32_e64 v2, v136, v2
	v_add_f32_e64 v3, v137, v3
	v_add_f32_e64 v2, v138, v2
	v_add_f32_e64 v3, v139, v3
	v_add_f32_e32 v2, v140, v2
	v_add_f32_e32 v3, v141, v3
	v_mfma_f32_32x32x16_bf16 v[80:95], v[10:13], v[32:35], v[80:95]
	v_add_f32_e64 v2, v108, v2
	v_add_f32_e64 v3, v109, v3
	v_add_f32_e64 v2, v142, v2
	v_add_f32_e64 v3, v143, v3
	v_add_f32_e64 v2, v110, v2
	v_add_f32_e64 v3, v111, v3
	v_add_f32_e32 v2, v192, v2
	v_add_f32_e32 v3, v193, v3
	v_mfma_f32_32x32x16_bf16 v[64:79], v[96:99], v[36:39], v[64:79]
	v_pk_add_f32 v[2:3], v[2:3], v[2:3] op_sel_hi:[0,1]
	v_mfma_f32_32x32x16_bf16 v[80:95], v[104:107], v[36:39], v[80:95]
	ds_read_b128 v[6:9], v0 offset:352
	ds_read_b128 v[10:13], v0 offset:320
	ds_read_b128 v[96:99], v0 offset:256
	ds_read_b128 v[100:103], v0 offset:288
	ds_read_b128 v[32:35], v0 offset:480
	ds_read_b128 v[36:39], v0 offset:448
	ds_read_b128 v[104:107], v0 offset:416
	ds_read_b128 v[108:111], v0 offset:384
	s_waitcnt lgkmcnt(4)
	s_waitcnt lgkmcnt(0)
	ds_read_b128 v[112:115], v234 offset:9312
	ds_read_b128 v[116:119], v234 offset:9280
	ds_read_b128 v[120:123], v234 offset:9216
	ds_read_b128 v[124:127], v234 offset:9248
	ds_read_b128 v[128:131], v234 offset:13920
	ds_read_b128 v[132:135], v234 offset:13888
	ds_read_b128 v[136:139], v234 offset:13856
	ds_read_b128 v[140:143], v234 offset:13824
	v_sub_f32_e32 v47, v31, v35
	v_sub_f32_e32 v46, v30, v34
	v_sub_f32_e32 v45, v29, v33
	v_sub_f32_e32 v44, v28, v32
	v_sub_f32_e32 v43, v27, v39
	v_sub_f32_e32 v42, v26, v38
	v_sub_f32_e32 v41, v25, v37
	v_sub_f32_e32 v40, v24, v36
	v_sub_f32_e32 v39, v23, v107
	v_sub_f32_e32 v38, v22, v106
	v_sub_f32_e32 v37, v21, v105
	v_sub_f32_e32 v36, v20, v104
	v_sub_f32_e32 v35, v19, v111
	v_sub_f32_e32 v34, v18, v110
	v_sub_f32_e32 v33, v17, v109
	v_sub_f32_e32 v32, v16, v108
	v_sub_f32_e32 v111, v63, v9
	v_sub_f32_e32 v110, v62, v8
	v_sub_f32_e32 v109, v61, v7
	v_sub_f32_e32 v108, v60, v6
	v_sub_f32_e32 v107, v59, v13
	v_sub_f32_e32 v106, v58, v12
	v_sub_f32_e32 v105, v57, v11
	v_sub_f32_e32 v104, v56, v10
	v_sub_f32_e32 v103, v55, v103
	v_sub_f32_e32 v102, v54, v102
	v_sub_f32_e32 v101, v53, v101
	v_sub_f32_e32 v100, v52, v100
	v_sub_f32_e32 v99, v51, v99
	v_sub_f32_e32 v98, v50, v98
	v_sub_f32_e32 v97, v49, v97
	v_sub_f32_e32 v96, v48, v96
	s_waitcnt lgkmcnt(4)
	s_waitcnt lgkmcnt(0)
	s_nop 0
	v_mfma_f32_32x32x16_bf16 v[32:47], v[140:143], v[144:147], v[32:47]
	v_mfma_f32_32x32x16_bf16 v[96:111], v[120:123], v[144:147], v[96:111]
	v_mfma_f32_32x32x16_bf16 v[96:111], v[124:127], v[148:151], v[96:111]
	v_mfma_f32_32x32x16_bf16 v[32:47], v[136:139], v[148:151], v[32:47]
	v_mfma_f32_32x32x16_bf16 v[96:111], v[116:119], v[152:155], v[96:111]
	v_mfma_f32_32x32x16_bf16 v[32:47], v[132:135], v[152:155], v[32:47]
	v_mfma_f32_32x32x16_bf16 v[96:111], v[112:115], v[156:159], v[96:111]
	ds_read_b64_tr_b16 v[6:7], v4 offset:49152
	ds_read_b64_tr_b16 v[8:9], v4 offset:50688
	ds_read_b64_tr_b16 v[10:11], v4 offset:52224
	ds_read_b64_tr_b16 v[12:13], v4 offset:53760
	ds_read_b64_tr_b16 v[112:113], v4 offset:49216
	ds_read_b64_tr_b16 v[114:115], v4 offset:50752
	ds_read_b64_tr_b16 v[116:117], v4 offset:52288
	ds_read_b64_tr_b16 v[118:119], v4 offset:53824
	v_mfma_f32_32x32x16_bf16 v[32:47], v[128:131], v[156:159], v[32:47]
	s_nop 2
	v_exp_f32_e32 v0, v96
	v_exp_f32_e32 v5, v97
	v_exp_f32_e32 v15, v98
	v_exp_f32_e32 v121, v99
	v_exp_f32_e32 v123, v100
	v_exp_f32_e32 v125, v101
	v_exp_f32_e32 v127, v102
	v_exp_f32_e32 v129, v103
	v_exp_f32_e32 v131, v104
	v_exp_f32_e32 v133, v105
	v_exp_f32_e32 v135, v106
	v_exp_f32_e32 v137, v107
	v_exp_f32_e32 v139, v108
	v_exp_f32_e32 v109, v109
	v_exp_f32_e32 v141, v110
	v_exp_f32_e32 v111, v111
	v_cvt_pk_bf16_f32 v96, v0, v5
	v_cvt_pk_bf16_f32 v97, v15, v121
	v_cvt_pk_bf16_f32 v98, v123, v125
	v_cvt_pk_bf16_f32 v99, v127, v129
	v_cvt_pk_bf16_f32 v100, v131, v133
	v_cvt_pk_bf16_f32 v101, v135, v137
	v_cvt_pk_bf16_f32 v102, v139, v109
	v_cvt_pk_bf16_f32 v103, v141, v111
	s_waitcnt lgkmcnt(0)
	v_add_f32_e32 v143, 0, v0
	v_mfma_f32_32x32x16_bf16 v[64:79], v[6:9], v[96:99], v[64:79]
	v_mfma_f32_32x32x16_bf16 v[64:79], v[10:13], v[100:103], v[64:79]
	v_mfma_f32_32x32x16_bf16 v[80:95], v[112:115], v[96:99], v[80:95]
	ds_read_b64_tr_b16 v[6:7], v4 offset:55296
	ds_read_b64_tr_b16 v[8:9], v4 offset:56832
	ds_read_b64_tr_b16 v[12:13], v4 offset:56896
	ds_read_b64_tr_b16 v[10:11], v4 offset:55360
	ds_read_b64_tr_b16 v[96:97], v4 offset:58368
	ds_read_b64_tr_b16 v[98:99], v4 offset:59904
	ds_read_b64_tr_b16 v[106:107], v4 offset:59968
	ds_read_b64_tr_b16 v[104:105], v4 offset:58432
	v_mfma_f32_32x32x16_bf16 v[80:95], v[116:119], v[100:103], v[80:95]
	v_exp_f32_e32 v4, v32
	v_exp_f32_e32 v14, v33
	v_exp_f32_e32 v120, v34
	v_exp_f32_e32 v122, v35
	v_exp_f32_e32 v124, v36
	v_exp_f32_e32 v126, v37
	v_exp_f32_e32 v128, v38
	v_exp_f32_e32 v130, v39
	v_exp_f32_e32 v132, v40
	v_exp_f32_e32 v134, v41
	v_exp_f32_e32 v136, v42
	v_exp_f32_e32 v138, v43
	v_exp_f32_e32 v108, v44
	v_exp_f32_e32 v140, v45
	v_exp_f32_e32 v110, v46
	v_exp_f32_e32 v2, v47
	v_cvt_pk_bf16_f32 v32, v4, v14
	v_cvt_pk_bf16_f32 v33, v120, v122
	v_cvt_pk_bf16_f32 v34, v124, v126
	v_cvt_pk_bf16_f32 v35, v128, v130
	v_cvt_pk_bf16_f32 v36, v132, v134
	v_cvt_pk_bf16_f32 v37, v136, v138
	v_cvt_pk_bf16_f32 v38, v108, v140
	v_cvt_pk_bf16_f32 v39, v110, v2
	s_waitcnt lgkmcnt(0)
	v_mov_b32_e32 v142, v1
	v_mfma_f32_32x32x16_bf16 v[64:79], v[6:9], v[32:35], v[64:79]
	v_add_f32_e64 v4, v4, v142
	v_add_f32_e64 v5, v5, v143
	v_add_f32_e64 v4, v14, v4
	v_add_f32_e64 v5, v15, v5
	v_add_f32_e64 v4, v120, v4
	v_add_f32_e64 v5, v121, v5
	v_add_f32_e32 v4, v122, v4
	v_add_f32_e32 v5, v123, v5
	v_mfma_f32_32x32x16_bf16 v[80:95], v[10:13], v[32:35], v[80:95]
	v_add_f32_e64 v4, v124, v4
	v_add_f32_e64 v5, v125, v5
	v_add_f32_e64 v4, v126, v4
	v_add_f32_e64 v5, v127, v5
	v_add_f32_e64 v4, v128, v4
	v_add_f32_e64 v5, v129, v5
	v_add_f32_e32 v4, v130, v4
	v_add_f32_e32 v5, v131, v5
	v_mfma_f32_32x32x16_bf16 v[64:79], v[96:99], v[36:39], v[64:79]
	v_add_f32_e64 v4, v132, v4
	v_add_f32_e64 v5, v133, v5
	v_add_f32_e64 v4, v134, v4
	v_add_f32_e64 v5, v135, v5
	v_add_f32_e64 v4, v136, v4
	v_add_f32_e64 v5, v137, v5
	s_nop 5
	v_mov_b64_e32 v[126:127], v[78:79]
	v_mfma_f32_32x32x16_bf16 v[80:95], v[104:107], v[36:39], v[80:95]
	v_add_f32_e64 v4, v138, v4
	v_add_f32_e64 v5, v139, v5
	v_mov_b64_e32 v[124:125], v[76:77]
	v_add_f32_e64 v4, v108, v4
	v_add_f32_e64 v5, v109, v5
	v_mov_b64_e32 v[122:123], v[74:75]
	v_add_f32_e32 v4, v140, v4
	v_add_f32_e32 v5, v141, v5
	v_mov_b64_e32 v[120:121], v[72:73]
	v_add_f32_e32 v4, v110, v4
	v_add_f32_e32 v5, v111, v5
	v_mov_b64_e32 v[110:111], v[78:79]
	v_add_f32_e32 v2, v2, v4
	v_add_f32_e32 v3, v3, v5
	s_nop 0
	v_mov_b64_e32 v[32:33], v[80:81]
	v_mov_b64_e32 v[142:143], v[94:95]
	v_add_f32_e32 v192, v2, v3
	v_mov_b64_e32 v[108:109], v[76:77]
	v_mov_b64_e32 v[106:107], v[74:75]
	v_mov_b64_e32 v[104:105], v[72:73]
	v_mov_b64_e32 v[102:103], v[70:71]
	v_mov_b64_e32 v[100:101], v[68:69]
	v_mov_b64_e32 v[98:99], v[66:67]
	v_mov_b64_e32 v[96:97], v[64:65]
	v_mov_b64_e32 v[34:35], v[82:83]
	v_mov_b64_e32 v[36:37], v[84:85]
	v_mov_b64_e32 v[38:39], v[86:87]
	v_mov_b64_e32 v[40:41], v[88:89]
	v_mov_b64_e32 v[42:43], v[90:91]
	v_mov_b64_e32 v[44:45], v[92:93]
	v_mov_b64_e32 v[46:47], v[94:95]
	v_mov_b64_e32 v[140:141], v[92:93]
	v_mov_b64_e32 v[138:139], v[90:91]
	v_mov_b64_e32 v[136:137], v[88:89]
	v_mov_b64_e32 v[134:135], v[86:87]
	v_mov_b64_e32 v[132:133], v[84:85]
	v_mov_b64_e32 v[130:131], v[82:83]
	v_mov_b64_e32 v[128:129], v[80:81]
	v_mov_b64_e32 v[118:119], v[70:71]
	v_mov_b64_e32 v[116:117], v[68:69]
	v_mov_b64_e32 v[114:115], v[66:67]
	v_mov_b64_e32 v[112:113], v[64:65]
